# 128 stolen w_in units (queue keeps 128 V^T + 128 plain = w_in stage ends in 2 plain rounds) + bank-aware scan regs + younger-half-only prio
# baseline (speedup 1.0000x reference)
.Lwsteal:
	s_cmp_lg_u32 s25, 0
	s_cbranch_scc1 .LBB0_236
	s_add_i32 s5, s24, 0xfffffeaa
	s_cmpk_lt_u32 s5, 0x80
	s_cbranch_scc0 .LBB0_236
	s_add_i32 s5, s5, 0x80
	s_lshr_b32 s20, s5, 2
	s_and_b32 s21, s5, 3
	s_min_u32 s5, s21, 1
	s_add_i32 s21, s21, s5
	s_add_i32 s5, s21, 5
	s_cmp_lt_u32 s21, 4
	s_cselect_b32 s22, s21, s5
	s_mov_b64 s[2:3], -1

.LBB0_671:
	s_or_b64 exec, exec, s[2:3]
	s_waitcnt vmcnt(0)
	v_readfirstlane_b32 s2, v2
	s_mov_b64 s[8:9], s[72:73]
	s_nop 0
	v_add_u32_e32 v0, s2, v0
	v_add_u32_e32 v2, 0x80, v0
	v_cmp_lt_i32_e32 vcc, 0xff, v0
	s_nop 1
	v_cndmask_b32_e32 v0, v0, v2, vcc
	v_cmp_gt_i32_e32 vcc, s62, v0
	v_cmp_le_i32_e64 s[2:3], s85, v0
	s_or_b64 s[4:5], vcc, s[2:3]
	s_nor_b64 s[10:11], s[4:5], s[72:73]
	s_and_saveexec_b64 s[4:5], s[10:11]
	s_cbranch_execz .LBB0_686
	s_mov_b32 s10, 0x1000000
	s_branch .LBB0_675

.LBB0_675:
	global_load_dword v2, v1, s[90:91] offset:192 sc1
	s_mov_b64 s[8:9], -1
	s_waitcnt vmcnt(0)
	v_cmp_lt_u32_e32 vcc, 0xff, v2
	s_cbranch_vccnz .LBB0_674
	s_cmp_lg_u32 s10, 0
	s_sleep 2
	s_cbranch_scc0 .LBB0_673
	global_load_dword v2, v1, s[90:91] offset:192 sc1
	s_waitcnt vmcnt(0)
	v_cmp_gt_u32_e32 vcc, 0x100, v2
	s_cbranch_vccz .LBB0_674
	s_sleep 2
	global_load_dword v2, v1, s[90:91] offset:192 sc1
	s_waitcnt vmcnt(0)
	v_cmp_gt_u32_e32 vcc, 0x100, v2
	s_cbranch_vccz .LBB0_674
	s_sleep 2
	global_load_dword v2, v1, s[90:91] offset:192 sc1
	s_waitcnt vmcnt(0)
	v_cmp_gt_u32_e32 vcc, 0x100, v2
	s_cbranch_vccz .LBB0_674
	s_sleep 2
	global_load_dword v2, v1, s[90:91] offset:192 sc1
	s_waitcnt vmcnt(0)
	v_cmp_gt_u32_e32 vcc, 0x100, v2
	s_cbranch_vccz .LBB0_674
	s_sleep 2
	global_load_dword v2, v1, s[90:91] offset:192 sc1
	s_waitcnt vmcnt(0)
	v_cmp_gt_u32_e32 vcc, 0x100, v2
	s_cbranch_vccz .LBB0_674
	s_sleep 2
	global_load_dword v2, v1, s[90:91] offset:192 sc1
	s_waitcnt vmcnt(0)
	v_cmp_gt_u32_e32 vcc, 0x100, v2
	s_cbranch_vccz .LBB0_674
	s_sleep 2
	global_load_dword v2, v1, s[90:91] offset:192 sc1
	s_waitcnt vmcnt(0)
	v_cmp_gt_u32_e32 vcc, 0x100, v2
	s_cbranch_vccz .LBB0_674
	s_sleep 2
	s_add_i32 s10, s10, -8
	s_mov_b64 s[8:9], 0
	s_branch .LBB0_674
